# IN GEMM K-loop: per-segment s_setprio flips removed, one static s_setprio 1 for waves 4-7 before the loop
# speedup vs baseline: 1.0452x; 1.0001x over previous
.LBB0_919:
	s_ashr_i32 s61, s60, 31
	s_lshl_b64 s[64:65], s[60:61], 19
	s_add_u32 s64, s28, s64
	s_addc_u32 s65, s29, s65
	s_and_b64 s[66:67], s[38:39], exec
	s_cselect_b32 s14, s65, s71
	s_cselect_b32 s24, s64, s70
	s_ashr_i32 s59, s58, 31
	s_lshl_b64 s[66:67], s[58:59], 19
	s_add_u32 s66, s1, s66
	s_addc_u32 s67, s4, s67
	s_and_b64 s[74:75], s[38:39], exec
	s_cselect_b32 s59, s67, s73
	s_cselect_b32 s61, s66, s72
	s_add_u32 s70, s70, 0x40080
	s_addc_u32 s71, s71, 0
	s_add_u32 s63, s72, 0x100
	v_mov_b32_e32 v4, 0
	s_addc_u32 vcc_lo, s73, 0
	s_mov_b32 vcc_hi, -2
	v_mov_b32_e32 v5, v4
	v_mov_b32_e32 v6, v4
	v_mov_b32_e32 v7, v4
	v_mov_b32_e32 v8, v4
	v_mov_b32_e32 v9, v4
	v_mov_b32_e32 v10, v4
	v_mov_b32_e32 v11, v4
	v_mov_b32_e32 v20, v4
	v_mov_b32_e32 v21, v4
	v_mov_b32_e32 v22, v4
	v_mov_b32_e32 v23, v4
	v_mov_b32_e32 v24, v4
	v_mov_b32_e32 v25, v4
	v_mov_b32_e32 v26, v4
	v_mov_b32_e32 v27, v4
	v_mov_b32_e32 v36, v4
	v_mov_b32_e32 v37, v4
	v_mov_b32_e32 v38, v4
	v_mov_b32_e32 v39, v4
	v_mov_b32_e32 v40, v4
	v_mov_b32_e32 v41, v4
	v_mov_b32_e32 v42, v4
	v_mov_b32_e32 v43, v4
	v_mov_b32_e32 v52, v4
	v_mov_b32_e32 v53, v4
	v_mov_b32_e32 v54, v4
	v_mov_b32_e32 v55, v4
	v_mov_b32_e32 v56, v4
	v_mov_b32_e32 v57, v4
	v_mov_b32_e32 v58, v4
	v_mov_b32_e32 v59, v4
	v_mov_b32_e32 v12, v4
	v_mov_b32_e32 v13, v4
	v_mov_b32_e32 v14, v4
	v_mov_b32_e32 v15, v4
	v_mov_b32_e32 v16, v4
	v_mov_b32_e32 v17, v4
	v_mov_b32_e32 v18, v4
	v_mov_b32_e32 v19, v4
	v_mov_b32_e32 v28, v4
	v_mov_b32_e32 v29, v4
	v_mov_b32_e32 v30, v4
	v_mov_b32_e32 v31, v4
	v_mov_b32_e32 v32, v4
	v_mov_b32_e32 v33, v4
	v_mov_b32_e32 v34, v4
	v_mov_b32_e32 v35, v4
	v_mov_b32_e32 v44, v4
	v_mov_b32_e32 v45, v4
	v_mov_b32_e32 v46, v4
	v_mov_b32_e32 v47, v4
	v_mov_b32_e32 v48, v4
	v_mov_b32_e32 v49, v4
	v_mov_b32_e32 v50, v4
	v_mov_b32_e32 v51, v4
	v_mov_b32_e32 v60, v4
	v_mov_b32_e32 v61, v4
	v_mov_b32_e32 v62, v4
	v_mov_b32_e32 v63, v4
	v_mov_b32_e32 v64, v4
	v_mov_b32_e32 v65, v4
	v_mov_b32_e32 v66, v4
	v_mov_b32_e32 v67, v4
	v_mov_b32_e32 v68, v4
	v_mov_b32_e32 v69, v4
	v_mov_b32_e32 v70, v4
	v_mov_b32_e32 v71, v4
	v_mov_b32_e32 v72, v4
	v_mov_b32_e32 v73, v4
	v_mov_b32_e32 v74, v4
	v_mov_b32_e32 v75, v4
	v_mov_b32_e32 v84, v4
	v_mov_b32_e32 v85, v4
	v_mov_b32_e32 v86, v4
	v_mov_b32_e32 v87, v4
	v_mov_b32_e32 v88, v4
	v_mov_b32_e32 v89, v4
	v_mov_b32_e32 v90, v4
	v_mov_b32_e32 v91, v4
	v_mov_b32_e32 v100, v4
	v_mov_b32_e32 v101, v4
	v_mov_b32_e32 v102, v4
	v_mov_b32_e32 v103, v4
	v_mov_b32_e32 v104, v4
	v_mov_b32_e32 v105, v4
	v_mov_b32_e32 v106, v4
	v_mov_b32_e32 v107, v4
	v_mov_b32_e32 v116, v4
	v_mov_b32_e32 v117, v4
	v_mov_b32_e32 v118, v4
	v_mov_b32_e32 v119, v4
	v_mov_b32_e32 v120, v4
	v_mov_b32_e32 v121, v4
	v_mov_b32_e32 v122, v4
	v_mov_b32_e32 v123, v4
	v_mov_b32_e32 v76, v4
	v_mov_b32_e32 v77, v4
	v_mov_b32_e32 v78, v4
	v_mov_b32_e32 v79, v4
	v_mov_b32_e32 v80, v4
	v_mov_b32_e32 v81, v4
	v_mov_b32_e32 v82, v4
	v_mov_b32_e32 v83, v4
	v_mov_b32_e32 v92, v4
	v_mov_b32_e32 v93, v4
	v_mov_b32_e32 v94, v4
	v_mov_b32_e32 v95, v4
	v_mov_b32_e32 v96, v4
	v_mov_b32_e32 v97, v4
	v_mov_b32_e32 v98, v4
	v_mov_b32_e32 v99, v4
	v_mov_b32_e32 v108, v4
	v_mov_b32_e32 v109, v4
	v_mov_b32_e32 v110, v4
	v_mov_b32_e32 v111, v4
	v_mov_b32_e32 v112, v4
	v_mov_b32_e32 v113, v4
	v_mov_b32_e32 v114, v4
	v_mov_b32_e32 v115, v4
	v_mov_b32_e32 v124, v4
	v_mov_b32_e32 v125, v4
	v_mov_b32_e32 v126, v4
	v_mov_b32_e32 v127, v4
	v_mov_b32_e32 v128, v4
	v_mov_b32_e32 v129, v4
	v_mov_b32_e32 v130, v4
	v_mov_b32_e32 v131, v4
	s_cmp_ge_u32 s80, 0x1000
	s_cbranch_scc0 .Lmy_prio_in
	s_setprio 1
.Lmy_prio_in:
.LBB0_920:
	s_add_u32 s2, s70, 0xfffc0080
	s_addc_u32 s3, s71, -1
	s_add_i32 s9, 0, 0x10000
	s_cmp_eq_u32 vcc_hi, 12
	s_cselect_b32 s75, s14, s3
	s_cselect_b32 s74, s24, s2
	s_cselect_b32 s73, s59, vcc_lo
	s_cselect_b32 s72, s61, s63
	s_add_i32 s0, 0, 0x14000
	s_add_i32 m0, s69, 0xc000
	s_nop 0
	global_load_lds_dwordx4 v172, s[70:71]
	s_add_i32 m0, s69, 0xe000
	s_nop 0
	global_load_lds_dwordx4 v174, s[70:71]
	v_add_u32_e32 v2, s9, v188
	ds_read_b128 v[132:135], v2
	ds_read_b128 v[136:139], v2 offset:1024
	ds_read_b128 v[140:143], v2 offset:2048
	ds_read_b128 v[144:147], v2 offset:3072
	v_add_u32_e32 v2, s0, v188
	ds_read_b128 v[148:151], v2
	ds_read_b128 v[152:155], v2 offset:1024
	ds_read_b128 v[156:159], v2 offset:2048
	ds_read_b128 v[160:163], v2 offset:3072
	v_lshl_add_u64 v[184:185], s[70:71], 0, v[172:173]
	ds_read_b128 v[176:179], v189
	ds_read_b128 v[180:183], v189 offset:1024
	ds_read_b128 v[198:201], v189 offset:2048
	ds_read_b128 v[202:205], v189 offset:3072
	ds_read_b128 v[206:209], v189 offset:4096
	ds_read_b128 v[210:213], v189 offset:5120
	ds_read_b128 v[214:217], v189 offset:6144
	ds_read_b128 v[218:221], v189 offset:7168
	v_lshl_add_u64 v[184:185], s[70:71], 0, v[174:175]
	s_waitcnt vmcnt(8)
	s_waitcnt lgkmcnt(0)
	s_barrier
	s_waitcnt lgkmcnt(0)
	v_mfma_f32_16x16x32_bf16 v[128:131], v[132:135], v[176:179], v[128:131]
	v_mfma_f32_16x16x32_bf16 v[124:127], v[140:143], v[176:179], v[124:127]
	v_mfma_f32_16x16x32_bf16 v[112:115], v[132:135], v[198:201], v[112:115]
	v_mfma_f32_16x16x32_bf16 v[108:111], v[140:143], v[198:201], v[108:111]
	v_mfma_f32_16x16x32_bf16 v[96:99], v[132:135], v[206:209], v[96:99]
	v_mfma_f32_16x16x32_bf16 v[92:95], v[140:143], v[206:209], v[92:95]
	v_mfma_f32_16x16x32_bf16 v[80:83], v[132:135], v[214:217], v[80:83]
	v_mfma_f32_16x16x32_bf16 v[76:79], v[140:143], v[214:217], v[76:79]
	v_mfma_f32_16x16x32_bf16 v[128:131], v[136:139], v[180:183], v[128:131]
	v_mfma_f32_16x16x32_bf16 v[124:127], v[144:147], v[180:183], v[124:127]
	v_mfma_f32_16x16x32_bf16 v[112:115], v[136:139], v[202:205], v[112:115]
	v_mfma_f32_16x16x32_bf16 v[108:111], v[144:147], v[202:205], v[108:111]
	v_mfma_f32_16x16x32_bf16 v[96:99], v[136:139], v[210:213], v[96:99]
	v_mfma_f32_16x16x32_bf16 v[92:95], v[144:147], v[210:213], v[92:95]
	v_mfma_f32_16x16x32_bf16 v[80:83], v[136:139], v[218:221], v[80:83]
	v_mfma_f32_16x16x32_bf16 v[76:79], v[144:147], v[218:221], v[76:79]
	v_mfma_f32_16x16x32_bf16 v[120:123], v[148:151], v[176:179], v[120:123]
	v_mfma_f32_16x16x32_bf16 v[116:119], v[156:159], v[176:179], v[116:119]
	v_mfma_f32_16x16x32_bf16 v[104:107], v[148:151], v[198:201], v[104:107]
	v_mfma_f32_16x16x32_bf16 v[100:103], v[156:159], v[198:201], v[100:103]
	v_mfma_f32_16x16x32_bf16 v[88:91], v[148:151], v[206:209], v[88:91]
	v_mfma_f32_16x16x32_bf16 v[84:87], v[156:159], v[206:209], v[84:87]
	v_mfma_f32_16x16x32_bf16 v[72:75], v[148:151], v[214:217], v[72:75]
	v_mfma_f32_16x16x32_bf16 v[68:71], v[156:159], v[214:217], v[68:71]
	v_mfma_f32_16x16x32_bf16 v[120:123], v[152:155], v[180:183], v[120:123]
	v_mfma_f32_16x16x32_bf16 v[116:119], v[160:163], v[180:183], v[116:119]
	v_mfma_f32_16x16x32_bf16 v[104:107], v[152:155], v[202:205], v[104:107]
	v_mfma_f32_16x16x32_bf16 v[100:103], v[160:163], v[202:205], v[100:103]
	v_mfma_f32_16x16x32_bf16 v[88:91], v[152:155], v[210:213], v[88:91]
	v_mfma_f32_16x16x32_bf16 v[84:87], v[160:163], v[210:213], v[84:87]
	v_mfma_f32_16x16x32_bf16 v[72:75], v[152:155], v[218:221], v[72:75]
	v_mfma_f32_16x16x32_bf16 v[68:71], v[160:163], v[218:221], v[68:71]
	s_barrier
	s_add_i32 s2, s9, s80
	s_mov_b32 m0, s2
	s_nop 0
	global_load_lds_dwordx4 v166, s[72:73]
	s_add_i32 m0, s2, 0x2000
	s_add_u32 s2, s72, 0x40000
	s_addc_u32 s3, s73, 0
	s_add_i32 s0, s0, s80
	global_load_lds_dwordx4 v170, s[72:73]
	s_mov_b32 m0, s0
	s_nop 0
	global_load_lds_dwordx4 v166, s[2:3]
	s_add_i32 m0, s0, 0x2000
	s_nop 0
	global_load_lds_dwordx4 v170, s[2:3]
	s_mov_b32 m0, s69
	s_nop 0
	global_load_lds_dwordx4 v164, s[74:75]
	s_mov_b32 m0, s81
	s_nop 0
	global_load_lds_dwordx4 v168, s[74:75]
	v_lshl_add_u64 v[184:185], s[72:73], 0, v[166:167]
	ds_read_b128 v[176:179], v189 offset:16384
	ds_read_b128 v[180:183], v189 offset:17408
	ds_read_b128 v[198:201], v189 offset:18432
	ds_read_b128 v[202:205], v189 offset:19456
	ds_read_b128 v[206:209], v189 offset:20480
	ds_read_b128 v[210:213], v189 offset:21504
	ds_read_b128 v[214:217], v189 offset:22528
	ds_read_b128 v[218:221], v189 offset:23552
	v_lshl_add_u64 v[190:191], s[72:73], 0, v[170:171]
	v_lshl_add_u64 v[222:223], s[2:3], 0, v[166:167]
	v_lshl_add_u64 v[224:225], s[74:75], 0, v[168:169]
	v_lshl_add_u64 v[222:223], s[2:3], 0, v[170:171]
	v_lshl_add_u64 v[222:223], s[74:75], 0, v[164:165]
	s_waitcnt vmcnt(8)
	s_waitcnt lgkmcnt(0)
	s_barrier
	s_waitcnt lgkmcnt(0)
	v_mfma_f32_16x16x32_bf16 v[64:67], v[132:135], v[176:179], v[64:67]
	v_mfma_f32_16x16x32_bf16 v[60:63], v[140:143], v[176:179], v[60:63]
	v_mfma_f32_16x16x32_bf16 v[48:51], v[132:135], v[198:201], v[48:51]
	v_mfma_f32_16x16x32_bf16 v[44:47], v[140:143], v[198:201], v[44:47]
	v_mfma_f32_16x16x32_bf16 v[32:35], v[132:135], v[206:209], v[32:35]
	v_mfma_f32_16x16x32_bf16 v[28:31], v[140:143], v[206:209], v[28:31]
	v_mfma_f32_16x16x32_bf16 v[16:19], v[132:135], v[214:217], v[16:19]
	v_mfma_f32_16x16x32_bf16 v[12:15], v[140:143], v[214:217], v[12:15]
	v_mfma_f32_16x16x32_bf16 v[64:67], v[136:139], v[180:183], v[64:67]
	v_mfma_f32_16x16x32_bf16 v[60:63], v[144:147], v[180:183], v[60:63]
	v_mfma_f32_16x16x32_bf16 v[48:51], v[136:139], v[202:205], v[48:51]
	v_mfma_f32_16x16x32_bf16 v[44:47], v[144:147], v[202:205], v[44:47]
	v_mfma_f32_16x16x32_bf16 v[32:35], v[136:139], v[210:213], v[32:35]
	v_mfma_f32_16x16x32_bf16 v[28:31], v[144:147], v[210:213], v[28:31]
	v_mfma_f32_16x16x32_bf16 v[16:19], v[136:139], v[218:221], v[16:19]
	v_mfma_f32_16x16x32_bf16 v[12:15], v[144:147], v[218:221], v[12:15]
	v_mfma_f32_16x16x32_bf16 v[56:59], v[148:151], v[176:179], v[56:59]
	v_mfma_f32_16x16x32_bf16 v[52:55], v[156:159], v[176:179], v[52:55]
	v_mfma_f32_16x16x32_bf16 v[40:43], v[148:151], v[198:201], v[40:43]
	v_mfma_f32_16x16x32_bf16 v[36:39], v[156:159], v[198:201], v[36:39]
	v_mfma_f32_16x16x32_bf16 v[24:27], v[148:151], v[206:209], v[24:27]
	v_mfma_f32_16x16x32_bf16 v[20:23], v[156:159], v[206:209], v[20:23]
	v_mfma_f32_16x16x32_bf16 v[8:11], v[148:151], v[214:217], v[8:11]
	v_mfma_f32_16x16x32_bf16 v[4:7], v[156:159], v[214:217], v[4:7]
	v_mfma_f32_16x16x32_bf16 v[56:59], v[152:155], v[180:183], v[56:59]
	v_mfma_f32_16x16x32_bf16 v[52:55], v[160:163], v[180:183], v[52:55]
	v_mfma_f32_16x16x32_bf16 v[40:43], v[152:155], v[202:205], v[40:43]
	v_mfma_f32_16x16x32_bf16 v[36:39], v[160:163], v[202:205], v[36:39]
	v_mfma_f32_16x16x32_bf16 v[24:27], v[152:155], v[210:213], v[24:27]
	v_mfma_f32_16x16x32_bf16 v[20:23], v[160:163], v[210:213], v[20:23]
	v_mfma_f32_16x16x32_bf16 v[8:11], v[152:155], v[218:221], v[8:11]
	v_mfma_f32_16x16x32_bf16 v[4:7], v[160:163], v[218:221], v[4:7]
	s_barrier
	s_add_i32 s0, 0, 0x18000
	s_add_i32 s9, 0, 0x1c000
	s_add_u32 s2, s74, 0x40000
	s_addc_u32 s3, s75, 0
	s_mov_b32 m0, s88
	s_nop 0
	global_load_lds_dwordx4 v164, s[2:3]
	s_mov_b32 m0, s89
	s_nop 0
	global_load_lds_dwordx4 v168, s[2:3]
	v_add_u32_e32 v2, s0, v188
	ds_read_b128 v[132:135], v2
	ds_read_b128 v[136:139], v2 offset:1024
	ds_read_b128 v[140:143], v2 offset:2048
	ds_read_b128 v[144:147], v2 offset:3072
	v_add_u32_e32 v2, s9, v188
	ds_read_b128 v[148:151], v2
	ds_read_b128 v[152:155], v2 offset:1024
	ds_read_b128 v[156:159], v2 offset:2048
	ds_read_b128 v[160:163], v2 offset:3072
	v_lshl_add_u64 v[226:227], s[2:3], 0, v[164:165]
	ds_read_b128 v[176:179], v189 offset:32768
	ds_read_b128 v[180:183], v189 offset:33792
	ds_read_b128 v[198:201], v189 offset:34816
	ds_read_b128 v[202:205], v189 offset:35840
	ds_read_b128 v[206:209], v189 offset:36864
	ds_read_b128 v[210:213], v189 offset:37888
	ds_read_b128 v[214:217], v189 offset:38912
	ds_read_b128 v[218:221], v189 offset:39936
	v_lshl_add_u64 v[226:227], s[2:3], 0, v[168:169]
	s_waitcnt vmcnt(8)
	s_waitcnt lgkmcnt(0)
	s_barrier
	s_waitcnt lgkmcnt(0)
	v_mfma_f32_16x16x32_bf16 v[128:131], v[132:135], v[176:179], v[128:131]
	v_mfma_f32_16x16x32_bf16 v[124:127], v[140:143], v[176:179], v[124:127]
	v_mfma_f32_16x16x32_bf16 v[112:115], v[132:135], v[198:201], v[112:115]
	v_mfma_f32_16x16x32_bf16 v[108:111], v[140:143], v[198:201], v[108:111]
	v_mfma_f32_16x16x32_bf16 v[96:99], v[132:135], v[206:209], v[96:99]
	v_mfma_f32_16x16x32_bf16 v[92:95], v[140:143], v[206:209], v[92:95]
	v_mfma_f32_16x16x32_bf16 v[80:83], v[132:135], v[214:217], v[80:83]
	v_mfma_f32_16x16x32_bf16 v[76:79], v[140:143], v[214:217], v[76:79]
	v_mfma_f32_16x16x32_bf16 v[128:131], v[136:139], v[180:183], v[128:131]
	v_mfma_f32_16x16x32_bf16 v[124:127], v[144:147], v[180:183], v[124:127]
	v_mfma_f32_16x16x32_bf16 v[112:115], v[136:139], v[202:205], v[112:115]
	v_mfma_f32_16x16x32_bf16 v[108:111], v[144:147], v[202:205], v[108:111]
	v_mfma_f32_16x16x32_bf16 v[96:99], v[136:139], v[210:213], v[96:99]
	v_mfma_f32_16x16x32_bf16 v[92:95], v[144:147], v[210:213], v[92:95]
	v_mfma_f32_16x16x32_bf16 v[80:83], v[136:139], v[218:221], v[80:83]
	v_mfma_f32_16x16x32_bf16 v[76:79], v[144:147], v[218:221], v[76:79]
	v_mfma_f32_16x16x32_bf16 v[120:123], v[148:151], v[176:179], v[120:123]
	v_mfma_f32_16x16x32_bf16 v[116:119], v[156:159], v[176:179], v[116:119]
	v_mfma_f32_16x16x32_bf16 v[104:107], v[148:151], v[198:201], v[104:107]
	v_mfma_f32_16x16x32_bf16 v[100:103], v[156:159], v[198:201], v[100:103]
	v_mfma_f32_16x16x32_bf16 v[88:91], v[148:151], v[206:209], v[88:91]
	v_mfma_f32_16x16x32_bf16 v[84:87], v[156:159], v[206:209], v[84:87]
	v_mfma_f32_16x16x32_bf16 v[72:75], v[148:151], v[214:217], v[72:75]
	v_mfma_f32_16x16x32_bf16 v[68:71], v[156:159], v[214:217], v[68:71]
	v_mfma_f32_16x16x32_bf16 v[120:123], v[152:155], v[180:183], v[120:123]
	v_mfma_f32_16x16x32_bf16 v[116:119], v[160:163], v[180:183], v[116:119]
	v_mfma_f32_16x16x32_bf16 v[104:107], v[152:155], v[202:205], v[104:107]
	v_mfma_f32_16x16x32_bf16 v[100:103], v[160:163], v[202:205], v[100:103]
	v_mfma_f32_16x16x32_bf16 v[88:91], v[152:155], v[210:213], v[88:91]
	v_mfma_f32_16x16x32_bf16 v[84:87], v[160:163], v[210:213], v[84:87]
	v_mfma_f32_16x16x32_bf16 v[72:75], v[152:155], v[218:221], v[72:75]
	v_mfma_f32_16x16x32_bf16 v[68:71], v[160:163], v[218:221], v[68:71]
	s_barrier
	s_add_u32 s98, s72, 0x80
	s_addc_u32 s99, s73, 0
	s_add_u32 s100, s74, 0x80
	s_addc_u32 s101, s75, 0
	s_add_i32 s0, s0, s80
	s_mov_b32 m0, s0
	s_nop 0
	global_load_lds_dwordx4 v166, s[98:99]
	s_add_i32 m0, s0, 0x2000
	s_add_u32 s2, s72, 0x40080
	s_addc_u32 s3, s73, 0
	s_add_i32 s0, s9, s80
	global_load_lds_dwordx4 v170, s[98:99]
	s_mov_b32 m0, s0
	s_nop 0
	global_load_lds_dwordx4 v166, s[2:3]
	s_add_i32 m0, s0, 0x2000
	s_nop 0
	global_load_lds_dwordx4 v170, s[2:3]
	s_mov_b32 m0, s92
	s_nop 0
	global_load_lds_dwordx4 v164, s[100:101]
	s_mov_b32 m0, s93
	s_nop 0
	global_load_lds_dwordx4 v168, s[100:101]
	v_lshl_add_u64 v[184:185], v[184:185], 0, s[26:27]
	ds_read_b128 v[176:179], v189 offset:49152
	ds_read_b128 v[180:183], v189 offset:50176
	ds_read_b128 v[198:201], v189 offset:51200
	ds_read_b128 v[202:205], v189 offset:52224
	ds_read_b128 v[206:209], v189 offset:53248
	ds_read_b128 v[210:213], v189 offset:54272
	ds_read_b128 v[214:217], v189 offset:55296
	ds_read_b128 v[218:221], v189 offset:56320
	v_lshl_add_u64 v[184:185], v[190:191], 0, s[26:27]
	v_lshl_add_u64 v[184:185], s[2:3], 0, v[166:167]
	v_lshl_add_u64 v[184:185], s[2:3], 0, v[170:171]
	v_lshl_add_u64 v[184:185], v[222:223], 0, s[26:27]
	v_lshl_add_u64 v[184:185], v[224:225], 0, s[26:27]
	s_waitcnt vmcnt(8)
	s_waitcnt lgkmcnt(0)
	s_barrier
	s_waitcnt lgkmcnt(0)
	v_mfma_f32_16x16x32_bf16 v[64:67], v[132:135], v[176:179], v[64:67]
	v_mfma_f32_16x16x32_bf16 v[60:63], v[140:143], v[176:179], v[60:63]
	v_mfma_f32_16x16x32_bf16 v[48:51], v[132:135], v[198:201], v[48:51]
	v_mfma_f32_16x16x32_bf16 v[44:47], v[140:143], v[198:201], v[44:47]
	v_mfma_f32_16x16x32_bf16 v[32:35], v[132:135], v[206:209], v[32:35]
	v_mfma_f32_16x16x32_bf16 v[28:31], v[140:143], v[206:209], v[28:31]
	v_mfma_f32_16x16x32_bf16 v[16:19], v[132:135], v[214:217], v[16:19]
	v_mfma_f32_16x16x32_bf16 v[12:15], v[140:143], v[214:217], v[12:15]
	v_mfma_f32_16x16x32_bf16 v[64:67], v[136:139], v[180:183], v[64:67]
	v_mfma_f32_16x16x32_bf16 v[60:63], v[144:147], v[180:183], v[60:63]
	v_mfma_f32_16x16x32_bf16 v[48:51], v[136:139], v[202:205], v[48:51]
	v_mfma_f32_16x16x32_bf16 v[44:47], v[144:147], v[202:205], v[44:47]
	v_mfma_f32_16x16x32_bf16 v[32:35], v[136:139], v[210:213], v[32:35]
	v_mfma_f32_16x16x32_bf16 v[28:31], v[144:147], v[210:213], v[28:31]
	v_mfma_f32_16x16x32_bf16 v[16:19], v[136:139], v[218:221], v[16:19]
	v_mfma_f32_16x16x32_bf16 v[12:15], v[144:147], v[218:221], v[12:15]
	v_mfma_f32_16x16x32_bf16 v[56:59], v[148:151], v[176:179], v[56:59]
	v_mfma_f32_16x16x32_bf16 v[52:55], v[156:159], v[176:179], v[52:55]
	v_mfma_f32_16x16x32_bf16 v[40:43], v[148:151], v[198:201], v[40:43]
	v_mfma_f32_16x16x32_bf16 v[36:39], v[156:159], v[198:201], v[36:39]
	v_mfma_f32_16x16x32_bf16 v[24:27], v[148:151], v[206:209], v[24:27]
	v_mfma_f32_16x16x32_bf16 v[20:23], v[156:159], v[206:209], v[20:23]
	v_mfma_f32_16x16x32_bf16 v[8:11], v[148:151], v[214:217], v[8:11]
	v_mfma_f32_16x16x32_bf16 v[4:7], v[156:159], v[214:217], v[4:7]
	v_mfma_f32_16x16x32_bf16 v[56:59], v[152:155], v[180:183], v[56:59]
	v_mfma_f32_16x16x32_bf16 v[52:55], v[160:163], v[180:183], v[52:55]
	v_mfma_f32_16x16x32_bf16 v[40:43], v[152:155], v[202:205], v[40:43]
	v_mfma_f32_16x16x32_bf16 v[36:39], v[160:163], v[202:205], v[36:39]
	v_mfma_f32_16x16x32_bf16 v[24:27], v[152:155], v[210:213], v[24:27]
	v_mfma_f32_16x16x32_bf16 v[20:23], v[160:163], v[210:213], v[20:23]
	v_mfma_f32_16x16x32_bf16 v[8:11], v[152:155], v[218:221], v[8:11]
	v_mfma_f32_16x16x32_bf16 v[4:7], v[160:163], v[218:221], v[4:7]
	s_barrier
	s_add_i32 vcc_hi, vcc_hi, 2
	s_add_u32 s70, s70, 0x100
	s_addc_u32 s71, s71, 0
	s_add_u32 s63, s63, 0x100
	s_addc_u32 vcc_lo, vcc_lo, 0
	s_cmp_gt_u32 vcc_hi, 13
	s_cbranch_scc0 .LBB0_920
	s_setprio 0
	s_and_b64 vcc, exec, s[52:53]
	s_cbranch_vccz .LBB0_923
	s_barrier
